# main GEMM K-loop: back-to-back s_setprio 0/1 pairs between the two MFMA groups of a phase removed (plus merged waits)
# baseline (speedup 1.0000x reference)
.LBB0_744:
	s_add_i32 s35, s10, 2
	s_add_u32 s37, s8, 0x80
	s_addc_u32 s11, s9, 0
	s_add_i32 s72, 0, 0x10000
	s_cmp_eq_u32 s65, s10
	s_cselect_b32 s11, s29, s11
	s_cselect_b32 s10, s28, s37
	v_add_u32_e32 v160, s72, v183
	s_cselect_b32 s81, s31, s34
	s_cselect_b32 s80, s30, s27
	s_add_i32 s37, 0, 0x14000
	ds_read_b128 v[130:133], v160
	ds_read_b128 v[134:137], v160 offset:1024
	ds_read_b128 v[156:159], v160 offset:2048
	ds_read_b128 v[186:189], v160 offset:3072
	v_add_u32_e32 v160, s37, v183
	ds_read_b128 v[190:193], v160
	ds_read_b128 v[194:197], v160 offset:1024
	ds_read_b128 v[198:201], v160 offset:2048
	ds_read_b128 v[202:205], v160 offset:3072
	v_lshl_add_u64 v[160:161], s[8:9], 0, v[150:151]
	s_add_i32 m0, s45, 0xc000
	ds_read_b128 v[206:209], v185
	ds_read_b128 v[210:213], v185 offset:1024
	ds_read_b128 v[214:217], v185 offset:2048
	ds_read_b128 v[218:221], v185 offset:3072
	ds_read_b128 v[222:225], v185 offset:4096
	ds_read_b128 v[226:229], v185 offset:5120
	ds_read_b128 v[230:233], v185 offset:6144
	ds_read_b128 v[234:237], v185 offset:7168
	global_load_lds_dwordx4 v[160:161], off
	v_lshl_add_u64 v[160:161], s[8:9], 0, v[152:153]
	s_add_i32 m0, s45, 0xe000
	s_nop 0
	global_load_lds_dwordx4 v[160:161], off
	s_waitcnt vmcnt(8) lgkmcnt(0)
	s_barrier
	s_setprio 1
	v_mfma_f32_16x16x32_bf16 v[126:129], v[130:133], v[206:209], v[126:129]
	v_mfma_f32_16x16x32_bf16 v[122:125], v[156:159], v[206:209], v[122:125]
	v_mfma_f32_16x16x32_bf16 v[110:113], v[130:133], v[214:217], v[110:113]
	v_mfma_f32_16x16x32_bf16 v[106:109], v[156:159], v[214:217], v[106:109]
	v_mfma_f32_16x16x32_bf16 v[94:97], v[130:133], v[222:225], v[94:97]
	v_mfma_f32_16x16x32_bf16 v[90:93], v[156:159], v[222:225], v[90:93]
	v_mfma_f32_16x16x32_bf16 v[78:81], v[130:133], v[230:233], v[78:81]
	v_mfma_f32_16x16x32_bf16 v[74:77], v[156:159], v[230:233], v[74:77]
	v_mfma_f32_16x16x32_bf16 v[126:129], v[134:137], v[210:213], v[126:129]
	v_mfma_f32_16x16x32_bf16 v[122:125], v[186:189], v[210:213], v[122:125]
	v_mfma_f32_16x16x32_bf16 v[110:113], v[134:137], v[218:221], v[110:113]
	v_mfma_f32_16x16x32_bf16 v[106:109], v[186:189], v[218:221], v[106:109]
	v_mfma_f32_16x16x32_bf16 v[94:97], v[134:137], v[226:229], v[94:97]
	v_mfma_f32_16x16x32_bf16 v[90:93], v[186:189], v[226:229], v[90:93]
	v_mfma_f32_16x16x32_bf16 v[78:81], v[134:137], v[234:237], v[78:81]
	v_mfma_f32_16x16x32_bf16 v[74:77], v[186:189], v[234:237], v[74:77]
	v_mfma_f32_16x16x32_bf16 v[118:121], v[190:193], v[206:209], v[118:121]
	v_mfma_f32_16x16x32_bf16 v[114:117], v[198:201], v[206:209], v[114:117]
	v_mfma_f32_16x16x32_bf16 v[102:105], v[190:193], v[214:217], v[102:105]
	v_mfma_f32_16x16x32_bf16 v[98:101], v[198:201], v[214:217], v[98:101]
	v_mfma_f32_16x16x32_bf16 v[86:89], v[190:193], v[222:225], v[86:89]
	v_mfma_f32_16x16x32_bf16 v[82:85], v[198:201], v[222:225], v[82:85]
	v_mfma_f32_16x16x32_bf16 v[70:73], v[190:193], v[230:233], v[70:73]
	v_mfma_f32_16x16x32_bf16 v[66:69], v[198:201], v[230:233], v[66:69]
	v_mfma_f32_16x16x32_bf16 v[118:121], v[194:197], v[210:213], v[118:121]
	v_mfma_f32_16x16x32_bf16 v[114:117], v[202:205], v[210:213], v[114:117]
	v_mfma_f32_16x16x32_bf16 v[102:105], v[194:197], v[218:221], v[102:105]
	v_mfma_f32_16x16x32_bf16 v[98:101], v[202:205], v[218:221], v[98:101]
	v_mfma_f32_16x16x32_bf16 v[86:89], v[194:197], v[226:229], v[86:89]
	v_mfma_f32_16x16x32_bf16 v[82:85], v[202:205], v[226:229], v[82:85]
	v_mfma_f32_16x16x32_bf16 v[70:73], v[194:197], v[234:237], v[70:73]
	v_mfma_f32_16x16x32_bf16 v[66:69], v[202:205], v[234:237], v[66:69]
	s_setprio 0
	s_barrier
	s_add_i32 s72, s72, s33
	v_lshl_add_u64 v[160:161], s[80:81], 0, v[0:1]
	s_mov_b32 m0, s72
	ds_read_b128 v[206:209], v185 offset:16384
	ds_read_b128 v[210:213], v185 offset:17408
	ds_read_b128 v[214:217], v185 offset:18432
	ds_read_b128 v[218:221], v185 offset:19456
	ds_read_b128 v[222:225], v185 offset:20480
	ds_read_b128 v[226:229], v185 offset:21504
	ds_read_b128 v[230:233], v185 offset:22528
	ds_read_b128 v[234:237], v185 offset:23552
	global_load_lds_dwordx4 v[160:161], off
	s_add_i32 m0, s72, 0x2000
	v_lshl_add_u64 v[238:239], s[80:81], 0, v[144:145]
	s_add_u32 s80, s80, s39
	s_addc_u32 s81, s81, 0
	s_add_i32 s37, s37, s33
	global_load_lds_dwordx4 v[238:239], off
	v_lshl_add_u64 v[240:241], s[80:81], 0, v[0:1]
	s_mov_b32 m0, s37
	v_lshl_add_u64 v[242:243], s[80:81], 0, v[144:145]
	global_load_lds_dwordx4 v[240:241], off
	s_add_i32 m0, s37, 0x2000
	v_lshl_add_u64 v[244:245], s[10:11], 0, v[146:147]
	global_load_lds_dwordx4 v[242:243], off
	s_mov_b32 m0, s45
	v_lshl_add_u64 v[246:247], s[10:11], 0, v[142:143]
	global_load_lds_dwordx4 v[244:245], off
	s_mov_b32 m0, s59
	s_nop 0
	global_load_lds_dwordx4 v[246:247], off
	s_waitcnt vmcnt(8) lgkmcnt(0)
	s_barrier
	s_setprio 1
	v_mfma_f32_16x16x32_bf16 v[62:65], v[130:133], v[206:209], v[62:65]
	v_mfma_f32_16x16x32_bf16 v[58:61], v[156:159], v[206:209], v[58:61]
	v_mfma_f32_16x16x32_bf16 v[46:49], v[130:133], v[214:217], v[46:49]
	v_mfma_f32_16x16x32_bf16 v[42:45], v[156:159], v[214:217], v[42:45]
	v_mfma_f32_16x16x32_bf16 v[30:33], v[130:133], v[222:225], v[30:33]
	v_mfma_f32_16x16x32_bf16 v[26:29], v[156:159], v[222:225], v[26:29]
	v_mfma_f32_16x16x32_bf16 v[14:17], v[130:133], v[230:233], v[14:17]
	v_mfma_f32_16x16x32_bf16 v[10:13], v[156:159], v[230:233], v[10:13]
	v_mfma_f32_16x16x32_bf16 v[62:65], v[134:137], v[210:213], v[62:65]
	v_mfma_f32_16x16x32_bf16 v[58:61], v[186:189], v[210:213], v[58:61]
	v_mfma_f32_16x16x32_bf16 v[46:49], v[134:137], v[218:221], v[46:49]
	v_mfma_f32_16x16x32_bf16 v[42:45], v[186:189], v[218:221], v[42:45]
	v_mfma_f32_16x16x32_bf16 v[30:33], v[134:137], v[226:229], v[30:33]
	v_mfma_f32_16x16x32_bf16 v[26:29], v[186:189], v[226:229], v[26:29]
	v_mfma_f32_16x16x32_bf16 v[14:17], v[134:137], v[234:237], v[14:17]
	v_mfma_f32_16x16x32_bf16 v[10:13], v[186:189], v[234:237], v[10:13]
	v_mfma_f32_16x16x32_bf16 v[54:57], v[190:193], v[206:209], v[54:57]
	v_mfma_f32_16x16x32_bf16 v[50:53], v[198:201], v[206:209], v[50:53]
	v_mfma_f32_16x16x32_bf16 v[38:41], v[190:193], v[214:217], v[38:41]
	v_mfma_f32_16x16x32_bf16 v[34:37], v[198:201], v[214:217], v[34:37]
	v_mfma_f32_16x16x32_bf16 v[22:25], v[190:193], v[222:225], v[22:25]
	v_mfma_f32_16x16x32_bf16 v[18:21], v[198:201], v[222:225], v[18:21]
	v_mfma_f32_16x16x32_bf16 v[6:9], v[190:193], v[230:233], v[6:9]
	v_mfma_f32_16x16x32_bf16 v[2:5], v[198:201], v[230:233], v[2:5]
	v_mfma_f32_16x16x32_bf16 v[54:57], v[194:197], v[210:213], v[54:57]
	v_mfma_f32_16x16x32_bf16 v[50:53], v[202:205], v[210:213], v[50:53]
	v_mfma_f32_16x16x32_bf16 v[38:41], v[194:197], v[218:221], v[38:41]
	v_mfma_f32_16x16x32_bf16 v[34:37], v[202:205], v[218:221], v[34:37]
	v_mfma_f32_16x16x32_bf16 v[22:25], v[194:197], v[226:229], v[22:25]
	v_mfma_f32_16x16x32_bf16 v[18:21], v[202:205], v[226:229], v[18:21]
	v_mfma_f32_16x16x32_bf16 v[6:9], v[194:197], v[234:237], v[6:9]
	v_mfma_f32_16x16x32_bf16 v[2:5], v[202:205], v[234:237], v[2:5]
	s_setprio 0
	s_barrier
	s_add_i32 s37, 0, 0x1c000
	v_add_u32_e32 v186, s66, v183
	v_add_u32_e32 v202, s37, v183
	ds_read_b128 v[130:133], v186
	ds_read_b128 v[134:137], v186 offset:1024
	ds_read_b128 v[156:159], v186 offset:2048
	ds_read_b128 v[186:189], v186 offset:3072
	ds_read_b128 v[190:193], v202
	ds_read_b128 v[194:197], v202 offset:1024
	ds_read_b128 v[198:201], v202 offset:2048
	ds_read_b128 v[202:205], v202 offset:3072
	s_add_u32 s10, s10, s0
	s_addc_u32 s11, s11, 0
	s_mov_b32 m0, s60
	v_lshl_add_u64 v[248:249], s[10:11], 0, v[146:147]
	ds_read_b128 v[206:209], v185 offset:32768
	ds_read_b128 v[210:213], v185 offset:33792
	ds_read_b128 v[214:217], v185 offset:34816
	ds_read_b128 v[218:221], v185 offset:35840
	ds_read_b128 v[222:225], v185 offset:36864
	ds_read_b128 v[226:229], v185 offset:37888
	ds_read_b128 v[230:233], v185 offset:38912
	ds_read_b128 v[234:237], v185 offset:39936
	global_load_lds_dwordx4 v[248:249], off
	v_lshl_add_u64 v[248:249], s[10:11], 0, v[142:143]
	s_mov_b32 m0, s61
	s_nop 0
	global_load_lds_dwordx4 v[248:249], off
	s_waitcnt vmcnt(8) lgkmcnt(0)
	s_barrier
	s_setprio 1
	v_mfma_f32_16x16x32_bf16 v[126:129], v[130:133], v[206:209], v[126:129]
	v_mfma_f32_16x16x32_bf16 v[122:125], v[156:159], v[206:209], v[122:125]
	v_mfma_f32_16x16x32_bf16 v[110:113], v[130:133], v[214:217], v[110:113]
	v_mfma_f32_16x16x32_bf16 v[106:109], v[156:159], v[214:217], v[106:109]
	v_mfma_f32_16x16x32_bf16 v[94:97], v[130:133], v[222:225], v[94:97]
	v_mfma_f32_16x16x32_bf16 v[90:93], v[156:159], v[222:225], v[90:93]
	v_mfma_f32_16x16x32_bf16 v[78:81], v[130:133], v[230:233], v[78:81]
	v_mfma_f32_16x16x32_bf16 v[74:77], v[156:159], v[230:233], v[74:77]
	v_mfma_f32_16x16x32_bf16 v[126:129], v[134:137], v[210:213], v[126:129]
	v_mfma_f32_16x16x32_bf16 v[122:125], v[186:189], v[210:213], v[122:125]
	v_mfma_f32_16x16x32_bf16 v[110:113], v[134:137], v[218:221], v[110:113]
	v_mfma_f32_16x16x32_bf16 v[106:109], v[186:189], v[218:221], v[106:109]
	v_mfma_f32_16x16x32_bf16 v[94:97], v[134:137], v[226:229], v[94:97]
	v_mfma_f32_16x16x32_bf16 v[90:93], v[186:189], v[226:229], v[90:93]
	v_mfma_f32_16x16x32_bf16 v[78:81], v[134:137], v[234:237], v[78:81]
	v_mfma_f32_16x16x32_bf16 v[74:77], v[186:189], v[234:237], v[74:77]
	v_mfma_f32_16x16x32_bf16 v[118:121], v[190:193], v[206:209], v[118:121]
	v_mfma_f32_16x16x32_bf16 v[114:117], v[198:201], v[206:209], v[114:117]
	v_mfma_f32_16x16x32_bf16 v[102:105], v[190:193], v[214:217], v[102:105]
	v_mfma_f32_16x16x32_bf16 v[98:101], v[198:201], v[214:217], v[98:101]
	v_mfma_f32_16x16x32_bf16 v[86:89], v[190:193], v[222:225], v[86:89]
	v_mfma_f32_16x16x32_bf16 v[82:85], v[198:201], v[222:225], v[82:85]
	v_mfma_f32_16x16x32_bf16 v[70:73], v[190:193], v[230:233], v[70:73]
	v_mfma_f32_16x16x32_bf16 v[66:69], v[198:201], v[230:233], v[66:69]
	v_mfma_f32_16x16x32_bf16 v[118:121], v[194:197], v[210:213], v[118:121]
	v_mfma_f32_16x16x32_bf16 v[114:117], v[202:205], v[210:213], v[114:117]
	v_mfma_f32_16x16x32_bf16 v[102:105], v[194:197], v[218:221], v[102:105]
	v_mfma_f32_16x16x32_bf16 v[98:101], v[202:205], v[218:221], v[98:101]
	v_mfma_f32_16x16x32_bf16 v[86:89], v[194:197], v[226:229], v[86:89]
	v_mfma_f32_16x16x32_bf16 v[82:85], v[202:205], v[226:229], v[82:85]
	v_mfma_f32_16x16x32_bf16 v[70:73], v[194:197], v[234:237], v[70:73]
	v_mfma_f32_16x16x32_bf16 v[66:69], v[202:205], v[234:237], v[66:69]
	s_setprio 0
	s_barrier
	s_add_i32 s10, s66, s33
	v_lshl_add_u64 v[160:161], v[160:161], 0, s[54:55]
	s_mov_b32 m0, s10
	ds_read_b128 v[206:209], v185 offset:49152
	ds_read_b128 v[210:213], v185 offset:50176
	ds_read_b128 v[214:217], v185 offset:51200
	ds_read_b128 v[218:221], v185 offset:52224
	ds_read_b128 v[222:225], v185 offset:53248
	ds_read_b128 v[226:229], v185 offset:54272
	ds_read_b128 v[230:233], v185 offset:55296
	ds_read_b128 v[234:237], v185 offset:56320
	global_load_lds_dwordx4 v[160:161], off
	v_lshl_add_u64 v[160:161], v[238:239], 0, s[54:55]
	s_add_i32 m0, s10, 0x2000
	s_add_i32 s10, s37, s33
	global_load_lds_dwordx4 v[160:161], off
	v_lshl_add_u64 v[160:161], v[240:241], 0, s[54:55]
	s_mov_b32 m0, s10
	s_nop 0
	global_load_lds_dwordx4 v[160:161], off
	v_lshl_add_u64 v[160:161], v[242:243], 0, s[54:55]
	s_add_i32 m0, s10, 0x2000
	s_nop 0
	global_load_lds_dwordx4 v[160:161], off
	v_lshl_add_u64 v[160:161], v[244:245], 0, s[54:55]
	s_mov_b32 m0, s63
	s_nop 0
	global_load_lds_dwordx4 v[160:161], off
	v_lshl_add_u64 v[160:161], v[246:247], 0, s[54:55]
	s_mov_b32 m0, s64
	s_nop 0
	global_load_lds_dwordx4 v[160:161], off
	s_waitcnt vmcnt(8) lgkmcnt(0)
	s_barrier
	s_setprio 1
	v_mfma_f32_16x16x32_bf16 v[62:65], v[130:133], v[206:209], v[62:65]
	v_mfma_f32_16x16x32_bf16 v[58:61], v[156:159], v[206:209], v[58:61]
	v_mfma_f32_16x16x32_bf16 v[46:49], v[130:133], v[214:217], v[46:49]
	v_mfma_f32_16x16x32_bf16 v[42:45], v[156:159], v[214:217], v[42:45]
	v_mfma_f32_16x16x32_bf16 v[30:33], v[130:133], v[222:225], v[30:33]
	v_mfma_f32_16x16x32_bf16 v[26:29], v[156:159], v[222:225], v[26:29]
	v_mfma_f32_16x16x32_bf16 v[14:17], v[130:133], v[230:233], v[14:17]
	v_mfma_f32_16x16x32_bf16 v[10:13], v[156:159], v[230:233], v[10:13]
	v_mfma_f32_16x16x32_bf16 v[62:65], v[134:137], v[210:213], v[62:65]
	v_mfma_f32_16x16x32_bf16 v[58:61], v[186:189], v[210:213], v[58:61]
	v_mfma_f32_16x16x32_bf16 v[46:49], v[134:137], v[218:221], v[46:49]
	v_mfma_f32_16x16x32_bf16 v[42:45], v[186:189], v[218:221], v[42:45]
	v_mfma_f32_16x16x32_bf16 v[30:33], v[134:137], v[226:229], v[30:33]
	v_mfma_f32_16x16x32_bf16 v[26:29], v[186:189], v[226:229], v[26:29]
	v_mfma_f32_16x16x32_bf16 v[14:17], v[134:137], v[234:237], v[14:17]
	v_mfma_f32_16x16x32_bf16 v[10:13], v[186:189], v[234:237], v[10:13]
	v_mfma_f32_16x16x32_bf16 v[54:57], v[190:193], v[206:209], v[54:57]
	v_mfma_f32_16x16x32_bf16 v[50:53], v[198:201], v[206:209], v[50:53]
	v_mfma_f32_16x16x32_bf16 v[38:41], v[190:193], v[214:217], v[38:41]
	v_mfma_f32_16x16x32_bf16 v[34:37], v[198:201], v[214:217], v[34:37]
	v_mfma_f32_16x16x32_bf16 v[22:25], v[190:193], v[222:225], v[22:25]
	v_mfma_f32_16x16x32_bf16 v[18:21], v[198:201], v[222:225], v[18:21]
	v_mfma_f32_16x16x32_bf16 v[6:9], v[190:193], v[230:233], v[6:9]
	v_mfma_f32_16x16x32_bf16 v[2:5], v[198:201], v[230:233], v[2:5]
	v_mfma_f32_16x16x32_bf16 v[54:57], v[194:197], v[210:213], v[54:57]
	v_mfma_f32_16x16x32_bf16 v[50:53], v[202:205], v[210:213], v[50:53]
	v_mfma_f32_16x16x32_bf16 v[38:41], v[194:197], v[218:221], v[38:41]
	v_mfma_f32_16x16x32_bf16 v[34:37], v[202:205], v[218:221], v[34:37]
	v_mfma_f32_16x16x32_bf16 v[22:25], v[194:197], v[226:229], v[22:25]
	v_mfma_f32_16x16x32_bf16 v[18:21], v[202:205], v[226:229], v[18:21]
	v_mfma_f32_16x16x32_bf16 v[6:9], v[194:197], v[234:237], v[6:9]
	v_mfma_f32_16x16x32_bf16 v[2:5], v[202:205], v[234:237], v[2:5]
	s_setprio 0
	s_barrier
	s_add_u32 s8, s8, 0x100
	s_addc_u32 s9, s9, 0
	s_add_u32 s27, s27, 0x100
	s_addc_u32 s34, s34, 0
	s_cmp_ge_u32 s35, s62
	s_mov_b32 s10, s35
	s_cbranch_scc0 .LBB0_744
	s_and_b64 vcc, exec, s[76:77]
	s_cbranch_vccz .LBB0_747
	s_barrier
